# speedup vs baseline: 1.0002x; 1.0002x over previous
; #define MFMA_FENCE() do { __builtin_amdgcn_sched_barrier(0); asm volatile("s_nop 15\n\ts_nop 15" ::: "memory"); __builtin_amdgcn_sched_barrier(0); } while (0)
; DEVI f32x16 mfma32(bf16x8 a, bf16x8 b, f32x16 c) { return __builtin_amdgcn_mfma_f32_32x32x16_bf16(a, b, c, 0, 0, 0); }
; template <bool SBK>
; __device__ __forceinline__ void attn_item(KP p, int layer, int b, int hh, int qt, char* smem, int tix) {
;     ...
;     const int kt = SBK ? (kt_hi - i) : (1 + i);
;     if (i + 1 < ntile) gload(SBK ? (kt - 1) : (kt + 1));
;     const u16* kb = Kb0 + (i & 1) * (KBUF_B / 2);
;     const u16* vb = Vb0 + (i & 1) * (VBUF_B / 2);
;     if (kt * 64 <= qmax_w && !sb_done) {
;       f32x16 s[2];
;       __builtin_amdgcn_s_setprio(1);
; #pragma unroll
;       for (int kb2 = 0; kb2 < 2; ++kb2) {
; #pragma unroll
;         for (int r = 0; r < 16; ++r) s[kb2][r] = 0.f;
; #pragma unroll
;         for (int ks = 0; ks < 4; ++ks) {
;           bf16x8 a = *(const bf16x8*)(kb + (kb2 * 32 + l32) * KST + c * 64 + ks * 16 + hf * 8);
;           s[kb2] = mfma32(a, qf[ks], s[kb2]);
;         }
;       }
;       __builtin_amdgcn_s_setprio(0);
;       bf16x8 pf[2][2];
;       MFMA_FENCE();
;       if (!SBK) {
;         const bool need_mask = (kt * 64 + 63 > qmin_w) || (kt == 1);
;         float mx = -1e30f;
; #pragma unroll
;         for (int kb2 = 0; kb2 < 2; ++kb2)
; #pragma unroll
;           for (int r = 0; r < 16; ++r) {
;             float t = s[kb2][r] * sc2;
;             if (need_mask) {
;               int kp = kt * 64 + kb2 * 32 + 8 * (r >> 2) + 4 * hf + (r & 3);
;               if (kp < PADF || kp > qpos) t = -1e30f;
;             }
;             s[kb2][r] = t;
;             mx = fmaxf(mx, t);
;           }
.LBB0_387:
	s_add_i32 s8, s22, 0x81
	s_bitcmp1_b32 s8, 0
	s_cselect_b32 s9, 0x4400, 0
	v_add3_u32 v161, v151, s9, v157
	ds_read_b128 v[194:197], v161
	ds_read_b128 v[198:201], v161 offset:32
	ds_read_b128 v[202:205], v161 offset:64
	ds_read_b128 v[206:209], v161 offset:96
	ds_read_b128 v[210:213], v161 offset:8704
	ds_read_b128 v[214:217], v161 offset:8736
	ds_read_b128 v[218:221], v161 offset:8768
	ds_read_b128 v[222:225], v161 offset:8800
	v_cmp_lt_u32_e64 s[4:5], s8, v0
	s_and_saveexec_b64 s[6:7], s[4:5]
	s_cbranch_execz .LBB0_389
	v_add_u32_e32 v66, s14, v140
	v_ashrrev_i32_e32 v67, 31, v66
	v_lshlrev_b64 v[66:67], 13, v[66:67]
	v_lshl_add_u64 v[66:67], v[146:147], 0, v[66:67]
	s_ashr_i32 s15, s14, 31
	global_load_dwordx4 v[118:121], v[66:67], off
	global_load_dwordx4 v[114:117], v[66:67], off offset:128
	v_lshl_add_u64 v[66:67], s[14:15], 1, v[144:145]
	v_add_co_u32_e32 v68, vcc, 0x208000, v66
	s_nop 1
	v_addc_co_u32_e32 v69, vcc, 0, v67, vcc
	global_load_dwordx4 v[122:125], v[66:67], off
	global_load_dwordx4 v[126:129], v[68:69], off
.LBB0_389:
	s_or_b64 exec, exec, s[6:7]
	s_sub_i32 s6, s14, 64
	v_cmp_le_i32_e32 vcc, s6, v141
	s_and_saveexec_b64 s[18:19], vcc
	s_cbranch_execz .LBB0_393
	s_bitcmp1_b32 s8, 0
	s_setprio 1
	s_cselect_b32 s7, 0x2200, 0
	s_lshl_b32 s15, s7, 1
	s_waitcnt lgkmcnt(7)
	v_mfma_f32_32x32x16_bf16 v[82:97], v[194:197], v[98:101], 0
	s_waitcnt lgkmcnt(6)
	v_mfma_f32_32x32x16_bf16 v[82:97], v[198:201], v[102:105], v[82:97]
	s_waitcnt lgkmcnt(5)
	v_mfma_f32_32x32x16_bf16 v[82:97], v[202:205], v[106:109], v[82:97]
	s_waitcnt lgkmcnt(4)
	v_mfma_f32_32x32x16_bf16 v[82:97], v[206:209], v[110:113], v[82:97]
	s_waitcnt lgkmcnt(3)
	v_mfma_f32_32x32x16_bf16 v[66:81], v[210:213], v[98:101], 0
	s_waitcnt lgkmcnt(2)
	v_mfma_f32_32x32x16_bf16 v[66:81], v[214:217], v[102:105], v[66:81]
	s_waitcnt lgkmcnt(1)
	v_mfma_f32_32x32x16_bf16 v[66:81], v[218:221], v[106:109], v[66:81]
	s_waitcnt lgkmcnt(0)
	v_mfma_f32_32x32x16_bf16 v[66:81], v[222:225], v[110:113], v[66:81]
	s_setprio 0
	v_add3_u32 v242, v152, s15, v159
	v_add_u32_e32 v243, 0x8800, v242
	ds_read2_b64 v[194:197], v243 offset1:2
	ds_read2_b64 v[198:201], v243 offset0:4 offset1:6
	ds_read2_b64 v[202:205], v243 offset0:8 offset1:10
	ds_read2_b64 v[206:209], v243 offset0:12 offset1:14
	v_add_u32_e32 v243, 0x9800, v242
	ds_read2_b64 v[210:213], v243 offset0:32 offset1:34
	ds_read2_b64 v[214:217], v243 offset0:36 offset1:38
	ds_read2_b64 v[218:221], v243 offset0:40 offset1:42
	ds_read2_b64 v[222:225], v243 offset0:44 offset1:46
	v_add_u32_e32 v243, 0xa800, v242
	ds_read2_b64 v[226:229], v243 offset0:64 offset1:66
	ds_read2_b64 v[230:233], v243 offset0:68 offset1:70
	ds_read2_b64 v[234:237], v243 offset0:72 offset1:74
	ds_read2_b64 v[238:241], v243 offset0:76 offset1:78
	s_nop 3
	s_add_i32 s7, s14, -1
	v_add_u32_e32 v161, s14, v134
	v_subrev_u32_e32 v162, 64, v161
	s_cmpk_lt_u32 s6, 0x70
	v_cmp_gt_i32_e32 vcc, s7, v148
	s_cbranch_vccz .Ldiff_fast
	s_cselect_b64 s[8:9], -1, 0
	v_cmp_gt_i32_e64 s[6:7], v162, v133
	s_or_b64 s[6:7], s[8:9], s[6:7]
	v_mul_f32_e32 v82, 0x3e38aa3b, v82
	s_and_b64 s[6:7], vcc, s[6:7]
	v_cndmask_b32_e64 v82, v82, v182, s[6:7]
	v_cmp_ge_i32_e64 s[6:7], v162, v133
	s_or_b64 s[6:7], s[8:9], s[6:7]
	v_mul_f32_e32 v83, 0x3e38aa3b, v83
	s_and_b64 s[6:7], vcc, s[6:7]
	v_subrev_u32_e32 v163, 62, v161
	v_cndmask_b32_e64 v83, v83, v182, s[6:7]
	v_cmp_gt_i32_e64 s[6:7], v163, v133
	s_or_b64 s[6:7], s[8:9], s[6:7]
	v_mul_f32_e32 v84, 0x3e38aa3b, v84
	s_and_b64 s[6:7], vcc, s[6:7]
	v_subrev_u32_e32 v163, 61, v161
	v_cndmask_b32_e64 v84, v84, v182, s[6:7]
	v_cmp_gt_i32_e64 s[6:7], v163, v133
	s_or_b64 s[6:7], s[8:9], s[6:7]
	v_mul_f32_e32 v85, 0x3e38aa3b, v85
	s_and_b64 s[6:7], vcc, s[6:7]
	v_subrev_u32_e32 v163, 56, v161
	v_cndmask_b32_e64 v85, v85, v182, s[6:7]
	v_cmp_gt_i32_e64 s[6:7], v163, v133
	s_or_b64 s[6:7], s[8:9], s[6:7]
	v_mul_f32_e32 v86, 0x3e38aa3b, v86
	s_and_b64 s[6:7], vcc, s[6:7]
	v_subrev_u32_e32 v163, 55, v161
	v_cndmask_b32_e64 v86, v86, v182, s[6:7]
	v_cmp_gt_i32_e64 s[6:7], v163, v133
	s_or_b64 s[6:7], s[8:9], s[6:7]
	v_mul_f32_e32 v87, 0x3e38aa3b, v87
	s_and_b64 s[6:7], vcc, s[6:7]
	v_subrev_u32_e32 v163, 54, v161
	v_cndmask_b32_e64 v87, v87, v182, s[6:7]
	v_cmp_gt_i32_e64 s[6:7], v163, v133
	s_or_b64 s[6:7], s[8:9], s[6:7]
	v_mul_f32_e32 v88, 0x3e38aa3b, v88
	s_and_b64 s[6:7], vcc, s[6:7]
	v_subrev_u32_e32 v163, 53, v161
	v_cndmask_b32_e64 v88, v88, v182, s[6:7]
	v_cmp_gt_i32_e64 s[6:7], v163, v133
	s_or_b64 s[6:7], s[8:9], s[6:7]
	v_mul_f32_e32 v89, 0x3e38aa3b, v89
	s_and_b64 s[6:7], vcc, s[6:7]
	v_subrev_u32_e32 v163, 48, v161
	v_cndmask_b32_e64 v89, v89, v182, s[6:7]
	v_cmp_gt_u32_e64 s[6:7], s53, v163
	v_cmp_gt_i32_e64 s[8:9], v163, v133
	s_or_b64 s[6:7], s[6:7], s[8:9]
	v_mul_f32_e32 v90, 0x3e38aa3b, v90
	s_and_b64 s[6:7], vcc, s[6:7]
	v_subrev_u32_e32 v163, 47, v161
	v_cndmask_b32_e64 v90, v90, v182, s[6:7]
	v_cmp_gt_u32_e64 s[6:7], s53, v163
	v_cmp_gt_i32_e64 s[8:9], v163, v133
	s_or_b64 s[6:7], s[6:7], s[8:9]
	v_mul_f32_e32 v91, 0x3e38aa3b, v91
	s_and_b64 s[6:7], vcc, s[6:7]
	v_subrev_u32_e32 v163, 46, v161
	v_cndmask_b32_e64 v91, v91, v182, s[6:7]
	v_cmp_gt_u32_e64 s[6:7], s53, v163
	v_cmp_gt_i32_e64 s[8:9], v163, v133
	s_or_b64 s[6:7], s[6:7], s[8:9]
	v_mul_f32_e32 v92, 0x3e38aa3b, v92
	s_and_b64 s[6:7], vcc, s[6:7]
	v_subrev_u32_e32 v163, 45, v161
	v_cndmask_b32_e64 v92, v92, v182, s[6:7]
	v_cmp_gt_u32_e64 s[6:7], s53, v163
	v_cmp_gt_i32_e64 s[8:9], v163, v133
	s_or_b64 s[6:7], s[6:7], s[8:9]
	v_mul_f32_e32 v93, 0x3e38aa3b, v93
; template <bool SBK>
; __device__ __forceinline__ void attn_item(KP p, int layer, int b, int hh, int qt, char* smem, int tix) {
;     ...
;         const bool need_mask = (kt * 64 + 63 > qmin_w) || (kt == 1);
;         float mx = -1e30f;
; #pragma unroll
;         for (int kb2 = 0; kb2 < 2; ++kb2)
; #pragma unroll
;           for (int r = 0; r < 16; ++r) {
;             float t = s[kb2][r] * sc2;
;             if (need_mask) {
;               int kp = kt * 64 + kb2 * 32 + 8 * (r >> 2) + 4 * hf + (r & 3);
;               if (kp < PADF || kp > qpos) t = -1e30f;
;             }
;             s[kb2][r] = t;
;             mx = fmaxf(mx, t);
;           }
	s_and_b64 s[6:7], vcc, s[6:7]
	v_subrev_u32_e32 v163, 40, v161
	v_cndmask_b32_e64 v93, v93, v182, s[6:7]
	v_cmp_gt_u32_e64 s[6:7], s53, v163
	v_cmp_gt_i32_e64 s[8:9], v163, v133
	s_or_b64 s[6:7], s[6:7], s[8:9]
	v_mul_f32_e32 v94, 0x3e38aa3b, v94
	s_and_b64 s[6:7], vcc, s[6:7]
	v_subrev_u32_e32 v163, 39, v161
	v_cndmask_b32_e64 v94, v94, v182, s[6:7]
	v_cmp_gt_u32_e64 s[6:7], s53, v163
	v_cmp_gt_i32_e64 s[8:9], v163, v133
	s_or_b64 s[6:7], s[6:7], s[8:9]
	v_mul_f32_e32 v95, 0x3e38aa3b, v95
	s_and_b64 s[6:7], vcc, s[6:7]
	v_subrev_u32_e32 v163, 38, v161
	v_cndmask_b32_e64 v95, v95, v182, s[6:7]
	v_cmp_gt_u32_e64 s[6:7], s53, v163
	v_cmp_gt_i32_e64 s[8:9], v163, v133
	s_or_b64 s[6:7], s[6:7], s[8:9]
	v_mul_f32_e32 v96, 0x3e38aa3b, v96
	s_and_b64 s[6:7], vcc, s[6:7]
	v_subrev_u32_e32 v163, 37, v161
	v_cndmask_b32_e64 v96, v96, v182, s[6:7]
	v_cmp_gt_u32_e64 s[6:7], s53, v163
	v_cmp_gt_i32_e64 s[8:9], v163, v133
	s_or_b64 s[6:7], s[6:7], s[8:9]
	v_mul_f32_e32 v97, 0x3e38aa3b, v97
	s_and_b64 s[6:7], vcc, s[6:7]
	v_subrev_u32_e32 v163, 32, v161
	v_cndmask_b32_e64 v97, v97, v182, s[6:7]
	v_cmp_gt_u32_e64 s[6:7], s53, v163
	v_cmp_gt_i32_e64 s[8:9], v163, v133
	s_or_b64 s[6:7], s[6:7], s[8:9]
	v_mul_f32_e32 v66, 0x3e38aa3b, v66
	s_and_b64 s[6:7], vcc, s[6:7]
	v_subrev_u32_e32 v163, 31, v161
	v_cndmask_b32_e64 v66, v66, v182, s[6:7]
	v_cmp_gt_u32_e64 s[6:7], s53, v163
	v_cmp_gt_i32_e64 s[8:9], v163, v133
	s_or_b64 s[6:7], s[6:7], s[8:9]
	v_mul_f32_e32 v67, 0x3e38aa3b, v67
	s_and_b64 s[6:7], vcc, s[6:7]
	v_subrev_u32_e32 v163, 30, v161
	v_cndmask_b32_e64 v67, v67, v182, s[6:7]
	v_cmp_gt_u32_e64 s[6:7], s53, v163
	v_cmp_gt_i32_e64 s[8:9], v163, v133
	s_or_b64 s[6:7], s[6:7], s[8:9]
	v_mul_f32_e32 v68, 0x3e38aa3b, v68
	s_and_b64 s[6:7], vcc, s[6:7]
	v_subrev_u32_e32 v163, 29, v161
	v_cndmask_b32_e64 v68, v68, v182, s[6:7]
	v_cmp_gt_u32_e64 s[6:7], s53, v163
	v_cmp_gt_i32_e64 s[8:9], v163, v133
	s_or_b64 s[6:7], s[6:7], s[8:9]
	v_mul_f32_e32 v69, 0x3e38aa3b, v69
	s_and_b64 s[6:7], vcc, s[6:7]
	v_subrev_u32_e32 v163, 24, v161
	v_cndmask_b32_e64 v69, v69, v182, s[6:7]
	v_cmp_gt_u32_e64 s[6:7], s53, v163
	v_cmp_gt_i32_e64 s[8:9], v163, v133
	s_or_b64 s[6:7], s[6:7], s[8:9]
	v_mul_f32_e32 v70, 0x3e38aa3b, v70
	s_and_b64 s[6:7], vcc, s[6:7]
	v_subrev_u32_e32 v163, 23, v161
	v_cndmask_b32_e64 v70, v70, v182, s[6:7]
	v_cmp_gt_u32_e64 s[6:7], s53, v163
	v_cmp_gt_i32_e64 s[8:9], v163, v133
	s_or_b64 s[6:7], s[6:7], s[8:9]
	v_mul_f32_e32 v71, 0x3e38aa3b, v71
	s_and_b64 s[6:7], vcc, s[6:7]
	v_subrev_u32_e32 v163, 22, v161
	v_cndmask_b32_e64 v71, v71, v182, s[6:7]
	v_cmp_gt_u32_e64 s[6:7], s53, v163
	v_cmp_gt_i32_e64 s[8:9], v163, v133
	s_or_b64 s[6:7], s[6:7], s[8:9]
	v_mul_f32_e32 v72, 0x3e38aa3b, v72
	s_and_b64 s[6:7], vcc, s[6:7]
	v_subrev_u32_e32 v163, 21, v161
	v_cndmask_b32_e64 v72, v72, v182, s[6:7]
	v_cmp_gt_u32_e64 s[6:7], s53, v163
	v_cmp_gt_i32_e64 s[8:9], v163, v133
	s_or_b64 s[6:7], s[6:7], s[8:9]
	v_mul_f32_e32 v73, 0x3e38aa3b, v73
	s_and_b64 s[6:7], vcc, s[6:7]
	v_add_u32_e32 v163, -16, v161
	v_cndmask_b32_e64 v73, v73, v182, s[6:7]
	v_cmp_gt_u32_e64 s[6:7], s53, v163
	v_cmp_gt_i32_e64 s[8:9], v163, v133
	s_or_b64 s[6:7], s[6:7], s[8:9]
	v_mul_f32_e32 v74, 0x3e38aa3b, v74
	s_and_b64 s[6:7], vcc, s[6:7]
	v_add_u32_e32 v163, -15, v161
	v_cndmask_b32_e64 v74, v74, v182, s[6:7]
	v_cmp_gt_u32_e64 s[6:7], s53, v163
	v_cmp_gt_i32_e64 s[8:9], v163, v133
	s_or_b64 s[6:7], s[6:7], s[8:9]
	v_mul_f32_e32 v75, 0x3e38aa3b, v75
	s_and_b64 s[6:7], vcc, s[6:7]
	v_add_u32_e32 v163, -14, v161
	v_cndmask_b32_e64 v75, v75, v182, s[6:7]
	v_cmp_gt_u32_e64 s[6:7], s53, v163
	v_cmp_gt_i32_e64 s[8:9], v163, v133
	s_or_b64 s[6:7], s[6:7], s[8:9]
	v_mul_f32_e32 v76, 0x3e38aa3b, v76
	s_and_b64 s[6:7], vcc, s[6:7]
	v_add_u32_e32 v163, -13, v161
	v_cndmask_b32_e64 v76, v76, v182, s[6:7]
	v_cmp_gt_u32_e64 s[6:7], s53, v163
	v_cmp_gt_i32_e64 s[8:9], v163, v133
	v_max3_f32 v162, v82, s23, v83
	s_or_b64 s[6:7], s[6:7], s[8:9]
	v_max3_f32 v162, v162, v84, v85
	v_mul_f32_e32 v77, 0x3e38aa3b, v77
	s_and_b64 s[6:7], vcc, s[6:7]
	v_add_u32_e32 v163, -8, v161
	v_max3_f32 v162, v162, v86, v87
	v_cndmask_b32_e64 v77, v77, v182, s[6:7]
	v_cmp_gt_u32_e64 s[6:7], s53, v163
	v_cmp_gt_i32_e64 s[8:9], v163, v133
	v_max3_f32 v162, v162, v88, v89
	s_or_b64 s[6:7], s[6:7], s[8:9]
	v_max3_f32 v162, v162, v90, v91
	v_mul_f32_e32 v78, 0x3e38aa3b, v78
	s_and_b64 s[6:7], vcc, s[6:7]
	v_add_u32_e32 v163, -7, v161
	v_max3_f32 v162, v162, v92, v93
	v_cndmask_b32_e64 v78, v78, v182, s[6:7]
	v_cmp_gt_u32_e64 s[6:7], s53, v163
	v_cmp_gt_i32_e64 s[8:9], v163, v133
	v_max3_f32 v162, v162, v94, v95
	s_or_b64 s[6:7], s[6:7], s[8:9]
	v_max3_f32 v162, v162, v96, v97
	v_mul_f32_e32 v79, 0x3e38aa3b, v79
	s_and_b64 s[6:7], vcc, s[6:7]
	v_add_u32_e32 v163, -6, v161
	v_max3_f32 v162, v162, v66, v67
	v_cndmask_b32_e64 v79, v79, v182, s[6:7]
	v_cmp_gt_u32_e64 s[6:7], s53, v163
	v_cmp_gt_i32_e64 s[8:9], v163, v133
	v_max3_f32 v162, v162, v68, v69
	s_or_b64 s[6:7], s[6:7], s[8:9]
	v_max3_f32 v162, v162, v70, v71
	v_mul_f32_e32 v80, 0x3e38aa3b, v80
	s_and_b64 s[6:7], vcc, s[6:7]
	v_add_u32_e32 v161, -5, v161
	v_max3_f32 v162, v162, v72, v73
	v_cndmask_b32_e64 v80, v80, v182, s[6:7]
	v_cmp_gt_u32_e64 s[6:7], s53, v161
	v_cmp_gt_i32_e64 s[8:9], v161, v133
	v_max3_f32 v162, v162, v74, v75
	s_or_b64 s[6:7], s[6:7], s[8:9]
	v_max3_f32 v162, v162, v76, v77
	v_mul_f32_e32 v81, 0x3e38aa3b, v81
	s_and_b64 vcc, vcc, s[6:7]
	v_max3_f32 v162, v162, v78, v79
	v_cndmask_b32_e32 v81, v81, v182, vcc
	v_max3_f32 v161, v162, v80, v81
